# nt hint on P0's once-read f32 weight loads as well
# speedup vs baseline: 1.0181x; 1.0052x over previous
; __device__ __forceinline__ void p0_prologue(const Args& a, LAS unsigned char* lds, int gw, int NGW, int wave, int lane) {
;     ...
;     for (int it = gw; it < NITEMS; it += NGW) {
;         int r = it;
;         if (r < 2 * I_GU) {
;             const bool second = r >= I_GU; if (second) r -= I_GU;
;             const int nblk = NGU / 32, kb = r / nblk, nb = r % nblk, n = nb * 32 + (lane & 31);
;             const float* wg = second ? a.w2g : a.w1g; const float* wu = second ? a.w2u : a.w1u;
;             const float* colp = (((n >> 7) & 1) ? wu : wg) + 128 * (n >> 8) + (n & 127);
;             transpose_item(colp, DFF, second ? a.g2 : a.g1, (bf16_t*)(ws + (second ? WS_W2GU : WS_W1GU)), DM, 0, kb * 64, nb * 32, scr, lane);
;             continue;
;         }
;         r -= 2 * I_GU;
;         if (r < 2 * I_D) {
;             const bool second = r >= I_D; if (second) r -= I_D;
;             const int nblk = DM / 32, kb = r / nblk, nb = r % nblk, n = nb * 32 + (lane & 31);
;             transpose_item((second ? a.w2d : a.w1d) + n, DM, nullptr, (bf16_t*)(ws + (second ? WS_W2D : WS_W1D)), DFF, 0, kb * 64, nb * 32, scr, lane);
;             continue;
;         }
;         r -= 2 * I_D;
;         if (r < I_IN) {
;             const int nblk = NIN / 32, kb = r / nblk, nb = r % nblk, n = nb * 32 + (lane & 31);
;             int src = -1;
;             if (n < 1536) src = n; else if (n < 2304) src = n + 8;
;             else if (n < 4352) { const int t = n - 2304; src = (((t >> 7) & 1) ? 3336 : 2312) + 128 * (t >> 8) + (t & 127); }
;             else if (n < 4360) src = n - 4352 + 1536;
;             transpose_item(src >= 0 ? a.win + src : nullptr, WIN_SRC, a.gmix, (bf16_t*)(ws + WS_WIN), DM, 0, kb * 64, nb * 32, scr, lane);
;             continue;
;         }
;         r -= I_IN;
;         if (r < 2 * I_BR) {
;             const bool second = r >= I_BR; if (second) r -= I_BR;
;             const int nblk = DM / 32, kb = r / nblk, nb = r % nblk, n = nb * 32 + (lane & 31);
;             transpose_item((second ? a.wba : a.wbm) + n, DM, nullptr, (bf16_t*)(ws + WS_WBR), DM, second ? 512 : 0, kb * 64, nb * 32, scr, lane);
;             continue;
;         }
;         r -= 2 * I_BR;
;         { const int nblk = DM / 32, kb = r / nblk, nb = r % nblk, n = nb * 32 + (lane & 31);
.LBB0_27:
	s_cmpk_gt_i32 s87, 0x15ff
	s_mov_b64 s[2:3], -1
	s_cbranch_scc0 .LBB0_330
	s_cmpk_gt_u32 s87, 0x20ff
	s_cbranch_scc0 .LBB0_263
	s_cmpk_gt_u32 s87, 0x29ff
	s_cbranch_scc0 .LBB0_162
	s_cmpk_gt_u32 s87, 0x2bff
	s_cbranch_scc0 .LBB0_96
	s_and_b32 s38, s33, 0x3e0
	v_or_b32_e32 v4, s38, v3
	s_and_b32 s2, s78, 0x7fffffc0
	v_lshlrev_b32_e32 v4, 2, v4
	s_add_i32 s6, s2, 0xffffa800
	v_lshl_add_u64 v[10:11], s[68:69], 0, v[4:5]
	v_or_b32_e32 v4, s6, v0
	v_mov_b32_e32 v12, 0
	v_cmp_ne_u32_e64 s[2:3], 1, v48
	s_andn2_b64 vcc, exec, s[30:31]
	v_mov_b32_e32 v13, 0
	s_cbranch_vccnz .LBB0_33
	v_lshlrev_b64 v[14:15], 12, v[4:5]
	v_lshl_add_u64 v[14:15], v[10:11], 0, v[14:15]
	global_load_dword v13, v[14:15], off nt
.LBB0_33:
	s_and_b64 vcc, exec, s[2:3]
	s_cbranch_vccnz .LBB0_35
	v_or_b32_e32 v14, 2, v4
	v_mov_b32_e32 v15, v5
	v_lshlrev_b64 v[14:15], 12, v[14:15]
	v_lshl_add_u64 v[14:15], v[10:11], 0, v[14:15]
	global_load_dword v12, v[14:15], off nt
.LBB0_35:
	v_mov_b32_e32 v14, 0
	s_and_b64 vcc, exec, s[2:3]
	v_mov_b32_e32 v15, 0
	s_cbranch_vccnz .LBB0_37
	v_or_b32_e32 v16, 4, v4
	v_mov_b32_e32 v17, v5
	v_lshlrev_b64 v[16:17], 12, v[16:17]
	v_lshl_add_u64 v[16:17], v[10:11], 0, v[16:17]
	global_load_dword v15, v[16:17], off nt
.LBB0_37:
	s_and_b64 vcc, exec, s[2:3]
	s_cbranch_vccnz .LBB0_39
	v_or_b32_e32 v16, 6, v4
	v_mov_b32_e32 v17, v5
	v_lshlrev_b64 v[16:17], 12, v[16:17]
	v_lshl_add_u64 v[16:17], v[10:11], 0, v[16:17]
	global_load_dword v14, v[16:17], off nt
.LBB0_39:
	v_mov_b32_e32 v16, 0
	s_and_b64 vcc, exec, s[2:3]
	v_mov_b32_e32 v17, 0
	s_cbranch_vccnz .LBB0_41
	v_or_b32_e32 v18, 8, v4
	v_mov_b32_e32 v19, v5
	v_lshlrev_b64 v[18:19], 12, v[18:19]
	v_lshl_add_u64 v[18:19], v[10:11], 0, v[18:19]
	global_load_dword v17, v[18:19], off nt
.LBB0_41:
	s_and_b64 vcc, exec, s[2:3]
	s_cbranch_vccnz .LBB0_43
	v_or_b32_e32 v18, 10, v4
	v_mov_b32_e32 v19, v5
	v_lshlrev_b64 v[18:19], 12, v[18:19]
	v_lshl_add_u64 v[18:19], v[10:11], 0, v[18:19]
	global_load_dword v16, v[18:19], off nt
.LBB0_43:
	v_mov_b32_e32 v18, 0
	s_and_b64 vcc, exec, s[2:3]
	v_mov_b32_e32 v19, 0
	s_cbranch_vccnz .LBB0_45
	v_or_b32_e32 v20, 12, v4
	v_mov_b32_e32 v21, v5
	v_lshlrev_b64 v[20:21], 12, v[20:21]
	v_lshl_add_u64 v[20:21], v[10:11], 0, v[20:21]
	global_load_dword v19, v[20:21], off nt
.LBB0_45:
	s_and_b64 vcc, exec, s[2:3]
	s_cbranch_vccnz .LBB0_47
	v_or_b32_e32 v20, 14, v4
	v_mov_b32_e32 v21, v5
	v_lshlrev_b64 v[20:21], 12, v[20:21]
	v_lshl_add_u64 v[20:21], v[10:11], 0, v[20:21]
	global_load_dword v18, v[20:21], off nt
.LBB0_47:
	v_mov_b32_e32 v20, 0
	s_and_b64 vcc, exec, s[2:3]
	v_mov_b32_e32 v21, 0
	s_cbranch_vccnz .LBB0_49
	v_or_b32_e32 v22, 16, v4
	v_mov_b32_e32 v23, v5
	v_lshlrev_b64 v[22:23], 12, v[22:23]
	v_lshl_add_u64 v[22:23], v[10:11], 0, v[22:23]
	global_load_dword v21, v[22:23], off nt
.LBB0_49:
	s_and_b64 vcc, exec, s[2:3]
	s_cbranch_vccnz .LBB0_51
	v_or_b32_e32 v22, 18, v4
	v_mov_b32_e32 v23, v5
	v_lshlrev_b64 v[22:23], 12, v[22:23]
	v_lshl_add_u64 v[22:23], v[10:11], 0, v[22:23]
	global_load_dword v20, v[22:23], off nt
.LBB0_51:
	v_mov_b32_e32 v22, 0
	s_and_b64 vcc, exec, s[2:3]
	v_mov_b32_e32 v23, 0
	s_cbranch_vccnz .LBB0_53
	v_or_b32_e32 v24, 20, v4
	v_mov_b32_e32 v25, v5
	v_lshlrev_b64 v[24:25], 12, v[24:25]
	v_lshl_add_u64 v[24:25], v[10:11], 0, v[24:25]
	global_load_dword v23, v[24:25], off nt
.LBB0_53:
	s_and_b64 vcc, exec, s[2:3]
	s_cbranch_vccnz .LBB0_55
	v_or_b32_e32 v24, 22, v4
	v_mov_b32_e32 v25, v5
	v_lshlrev_b64 v[24:25], 12, v[24:25]
	v_lshl_add_u64 v[24:25], v[10:11], 0, v[24:25]
	global_load_dword v22, v[24:25], off nt
.LBB0_55:
	v_mov_b32_e32 v24, 0
	s_and_b64 vcc, exec, s[2:3]
	v_mov_b32_e32 v25, 0
	s_cbranch_vccnz .LBB0_57
	v_or_b32_e32 v26, 24, v4
	v_mov_b32_e32 v27, v5
	v_lshlrev_b64 v[26:27], 12, v[26:27]
	v_lshl_add_u64 v[26:27], v[10:11], 0, v[26:27]
	global_load_dword v25, v[26:27], off nt
.LBB0_57:
	s_and_b64 vcc, exec, s[2:3]
	s_cbranch_vccnz .LBB0_59
	v_or_b32_e32 v26, 26, v4
	v_mov_b32_e32 v27, v5
	v_lshlrev_b64 v[26:27], 12, v[26:27]
	v_lshl_add_u64 v[26:27], v[10:11], 0, v[26:27]
	global_load_dword v24, v[26:27], off nt
.LBB0_59:
	v_mov_b32_e32 v26, 0
	s_and_b64 vcc, exec, s[2:3]
	v_mov_b32_e32 v27, 0
	s_cbranch_vccnz .LBB0_61
	v_or_b32_e32 v28, 28, v4
	v_mov_b32_e32 v29, v5
	v_lshlrev_b64 v[28:29], 12, v[28:29]
	v_lshl_add_u64 v[28:29], v[10:11], 0, v[28:29]
	global_load_dword v27, v[28:29], off nt
; #define LAS __attribute__((address_space(3)))
; __device__ __forceinline__ void transpose_item(const float* colp, int N, const float* gk, bf16_t* WT, int ldw, int koff, int k0, int n0, LAS float* scr, int lane) {
;     float v[32];
; #pragma unroll
;     for (int i = 0; i < 32; ++i) { const int kk = 2 * i + (lane >> 5); v[i] = colp ? colp[(size_t)(k0 + kk) * N] : 0.f; }
; __device__ __forceinline__ void p0_prologue(const Args& a, LAS unsigned char* lds, int gw, int NGW, int wave, int lane) {
;     ...
;         r -= 2 * I_BR;
;         { const int nblk = DM / 32, kb = r / nblk, nb = r % nblk, n = nb * 32 + (lane & 31);
;           transpose_item(a.wo + n, DM, nullptr, (bf16_t*)(ws + WS_WO), DM, 0, kb * 64, nb * 32, scr, lane); }
.LBB0_61:
	s_and_b64 vcc, exec, s[2:3]
	s_cbranch_vccnz .LBB0_63
	v_or_b32_e32 v28, 30, v4
	v_mov_b32_e32 v29, v5
	v_lshlrev_b64 v[28:29], 12, v[28:29]
	v_lshl_add_u64 v[28:29], v[10:11], 0, v[28:29]
	global_load_dword v26, v[28:29], off nt
.LBB0_63:
	v_mov_b32_e32 v28, 0
	s_and_b64 vcc, exec, s[2:3]
	v_mov_b32_e32 v29, 0
	s_cbranch_vccnz .LBB0_65
	v_or_b32_e32 v50, 32, v4
	v_mov_b32_e32 v51, v5
	v_lshlrev_b64 v[50:51], 12, v[50:51]
	v_lshl_add_u64 v[50:51], v[10:11], 0, v[50:51]
	global_load_dword v29, v[50:51], off nt
.LBB0_65:
	s_and_b64 vcc, exec, s[2:3]
	s_cbranch_vccnz .LBB0_67
	v_or_b32_e32 v50, 34, v4
	v_mov_b32_e32 v51, v5
	v_lshlrev_b64 v[50:51], 12, v[50:51]
	v_lshl_add_u64 v[50:51], v[10:11], 0, v[50:51]
	global_load_dword v28, v[50:51], off nt
.LBB0_67:
	v_mov_b32_e32 v49, 0
	s_and_b64 vcc, exec, s[2:3]
	v_mov_b32_e32 v50, 0
	s_cbranch_vccnz .LBB0_69
	v_or_b32_e32 v50, 36, v4
	v_mov_b32_e32 v51, v5
	v_lshlrev_b64 v[50:51], 12, v[50:51]
	v_lshl_add_u64 v[50:51], v[10:11], 0, v[50:51]
	global_load_dword v50, v[50:51], off nt
.LBB0_69:
	s_and_b64 vcc, exec, s[2:3]
	s_cbranch_vccnz .LBB0_71
	v_or_b32_e32 v52, 38, v4
	v_mov_b32_e32 v53, v5
	v_lshlrev_b64 v[52:53], 12, v[52:53]
	v_lshl_add_u64 v[52:53], v[10:11], 0, v[52:53]
	global_load_dword v49, v[52:53], off nt
.LBB0_71:
	v_mov_b32_e32 v51, 0
	s_and_b64 vcc, exec, s[2:3]
	v_mov_b32_e32 v52, 0
	s_cbranch_vccnz .LBB0_73
	v_or_b32_e32 v52, 40, v4
	v_mov_b32_e32 v53, v5
	v_lshlrev_b64 v[52:53], 12, v[52:53]
	v_lshl_add_u64 v[52:53], v[10:11], 0, v[52:53]
	global_load_dword v52, v[52:53], off nt
.LBB0_73:
	s_and_b64 vcc, exec, s[2:3]
	s_cbranch_vccnz .LBB0_75
	v_or_b32_e32 v54, 42, v4
	v_mov_b32_e32 v55, v5
	v_lshlrev_b64 v[54:55], 12, v[54:55]
	v_lshl_add_u64 v[54:55], v[10:11], 0, v[54:55]
	global_load_dword v51, v[54:55], off nt
.LBB0_75:
	v_mov_b32_e32 v53, 0
	s_and_b64 vcc, exec, s[2:3]
	v_mov_b32_e32 v54, 0
	s_cbranch_vccnz .LBB0_77
	v_or_b32_e32 v54, 44, v4
	v_mov_b32_e32 v55, v5
	v_lshlrev_b64 v[54:55], 12, v[54:55]
	v_lshl_add_u64 v[54:55], v[10:11], 0, v[54:55]
	global_load_dword v54, v[54:55], off nt
.LBB0_77:
	s_and_b64 vcc, exec, s[2:3]
	s_cbranch_vccnz .LBB0_79
	v_or_b32_e32 v56, 46, v4
	v_mov_b32_e32 v57, v5
	v_lshlrev_b64 v[56:57], 12, v[56:57]
	v_lshl_add_u64 v[56:57], v[10:11], 0, v[56:57]
	global_load_dword v53, v[56:57], off nt
.LBB0_79:
	v_mov_b32_e32 v55, 0
	s_and_b64 vcc, exec, s[2:3]
	v_mov_b32_e32 v56, 0
	s_cbranch_vccnz .LBB0_81
	v_or_b32_e32 v56, 48, v4
	v_mov_b32_e32 v57, v5
	v_lshlrev_b64 v[56:57], 12, v[56:57]
	v_lshl_add_u64 v[56:57], v[10:11], 0, v[56:57]
	global_load_dword v56, v[56:57], off nt
.LBB0_81:
	s_and_b64 vcc, exec, s[2:3]
	s_cbranch_vccnz .LBB0_83
	v_or_b32_e32 v58, 50, v4
	v_mov_b32_e32 v59, v5
	v_lshlrev_b64 v[58:59], 12, v[58:59]
	v_lshl_add_u64 v[58:59], v[10:11], 0, v[58:59]
	global_load_dword v55, v[58:59], off nt
.LBB0_83:
	v_mov_b32_e32 v57, 0
	s_and_b64 vcc, exec, s[2:3]
	v_mov_b32_e32 v58, 0
	s_cbranch_vccnz .LBB0_85
	v_or_b32_e32 v58, 52, v4
	v_mov_b32_e32 v59, v5
	v_lshlrev_b64 v[58:59], 12, v[58:59]
	v_lshl_add_u64 v[58:59], v[10:11], 0, v[58:59]
	global_load_dword v58, v[58:59], off nt
.LBB0_85:
	s_and_b64 vcc, exec, s[2:3]
	s_cbranch_vccnz .LBB0_87
	v_or_b32_e32 v60, 54, v4
	v_mov_b32_e32 v61, v5
	v_lshlrev_b64 v[60:61], 12, v[60:61]
	v_lshl_add_u64 v[60:61], v[10:11], 0, v[60:61]
	global_load_dword v57, v[60:61], off nt
.LBB0_87:
	v_mov_b32_e32 v59, 0
	s_and_b64 vcc, exec, s[2:3]
	v_mov_b32_e32 v60, 0
	s_cbranch_vccnz .LBB0_89
	v_or_b32_e32 v60, 56, v4
	v_mov_b32_e32 v61, v5
	v_lshlrev_b64 v[60:61], 12, v[60:61]
	v_lshl_add_u64 v[60:61], v[10:11], 0, v[60:61]
	global_load_dword v60, v[60:61], off nt
.LBB0_89:
	s_and_b64 vcc, exec, s[2:3]
	s_cbranch_vccnz .LBB0_91
	v_or_b32_e32 v62, 58, v4
	v_mov_b32_e32 v63, v5
	v_lshlrev_b64 v[62:63], 12, v[62:63]
	v_lshl_add_u64 v[62:63], v[10:11], 0, v[62:63]
	global_load_dword v59, v[62:63], off nt
.LBB0_91:
	v_mov_b32_e32 v61, 0
	s_and_b64 vcc, exec, s[2:3]
	v_mov_b32_e32 v62, 0
	s_cbranch_vccnz .LBB0_93
	v_or_b32_e32 v62, 60, v4
	v_mov_b32_e32 v63, v5
	v_lshlrev_b64 v[62:63], 12, v[62:63]
	v_lshl_add_u64 v[62:63], v[10:11], 0, v[62:63]
	global_load_dword v62, v[62:63], off nt
.LBB0_93:
	s_and_b64 vcc, exec, s[2:3]
	s_cbranch_vccnz .LBB0_95
	v_or_b32_e32 v4, 62, v4
	v_lshlrev_b64 v[64:65], 12, v[4:5]
	v_lshl_add_u64 v[10:11], v[10:11], 0, v[64:65]
	global_load_dword v61, v[10:11], off nt

; #define LAS __attribute__((address_space(3)))
; __device__ __forceinline__ void transpose_item(const float* colp, int N, const float* gk, bf16_t* WT, int ldw, int koff, int k0, int n0, LAS float* scr, int lane) {
;     float v[32];
; #pragma unroll
;     for (int i = 0; i < 32; ++i) { const int kk = 2 * i + (lane >> 5); v[i] = colp ? colp[(size_t)(k0 + kk) * N] : 0.f; }
; __device__ __forceinline__ void p0_prologue(const Args& a, LAS unsigned char* lds, int gw, int NGW, int wave, int lane) {
;     ...
;         r -= I_IN;
;         if (r < 2 * I_BR) {
;             const bool second = r >= I_BR; if (second) r -= I_BR;
;             const int nblk = DM / 32, kb = r / nblk, nb = r % nblk, n = nb * 32 + (lane & 31);
;             transpose_item((second ? a.wba : a.wbm) + n, DM, nullptr, (bf16_t*)(ws + WS_WBR), DM, second ? 512 : 0, kb * 64, nb * 32, scr, lane);
;             continue;
.LBB0_96:
	s_and_b64 vcc, exec, s[2:3]
	s_cbranch_vccz .LBB0_427
	s_cmpk_gt_u32 s87, 0x2aff
	s_cselect_b64 s[38:39], -1, 0
	s_and_b64 s[2:3], s[38:39], exec
	s_cselect_b32 s2, s80, 0xffffd600
	s_add_i32 s40, s2, s87
	s_lshl_b32 s2, s40, 5
	s_and_b32 s6, s2, 0x3e0
	s_and_b64 s[2:3], s[38:39], exec
	s_cselect_b32 s3, s67, s65
	s_cselect_b32 s2, s66, s64
	s_lshl_b32 s40, s40, 1
	v_or_b32_e32 v4, s6, v3
	s_and_b32 s42, s40, 0x7fffffc0
	v_lshlrev_b32_e32 v4, 2, v4
	s_cmp_lg_u64 s[2:3], 0
	v_lshl_add_u64 v[10:11], s[2:3], 0, v[4:5]
	s_cselect_b64 s[40:41], -1, 0
	s_cmp_eq_u64 s[2:3], 0
	v_or_b32_e32 v4, s42, v0
	v_mov_b32_e32 v13, 0
	v_mov_b32_e32 v12, 0
	s_cbranch_scc1 .LBB0_99
	v_lshlrev_b64 v[14:15], 12, v[4:5]
	v_lshl_add_u64 v[14:15], v[10:11], 0, v[14:15]
	global_load_dword v12, v[14:15], off nt
.LBB0_99:
	v_cndmask_b32_e64 v14, 0, 1, s[40:41]
	v_cmp_ne_u32_e64 s[2:3], 1, v14
	s_andn2_b64 vcc, exec, s[40:41]
	s_cbranch_vccnz .LBB0_101
	v_or_b32_e32 v14, 2, v4
	v_mov_b32_e32 v15, v5
	v_lshlrev_b64 v[14:15], 12, v[14:15]
	v_lshl_add_u64 v[14:15], v[10:11], 0, v[14:15]
	global_load_dword v13, v[14:15], off nt

; #define LAS __attribute__((address_space(3)))
; __device__ __forceinline__ void transpose_item(const float* colp, int N, const float* gk, bf16_t* WT, int ldw, int koff, int k0, int n0, LAS float* scr, int lane) {
;     float v[32];
; #pragma unroll
;     for (int i = 0; i < 32; ++i) { const int kk = 2 * i + (lane >> 5); v[i] = colp ? colp[(size_t)(k0 + kk) * N] : 0.f; }
; __device__ __forceinline__ void p0_prologue(const Args& a, LAS unsigned char* lds, int gw, int NGW, int wave, int lane) {
;     ...
;         r -= 2 * I_D;
;         if (r < I_IN) {
;             const int nblk = NIN / 32, kb = r / nblk, nb = r % nblk, n = nb * 32 + (lane & 31);
;             int src = -1;
;             if (n < 1536) src = n; else if (n < 2304) src = n + 8;
;             else if (n < 4352) { const int t = n - 2304; src = (((t >> 7) & 1) ? 3336 : 2312) + 128 * (t >> 8) + (t & 127); }
;             else if (n < 4360) src = n - 4352 + 1536;
;             transpose_item(src >= 0 ? a.win + src : nullptr, WIN_SRC, a.gmix, (bf16_t*)(ws + WS_WIN), DM, 0, kb * 64, nb * 32, scr, lane);
.LBB0_173:
	s_lshl_b32 s2, s6, 6
	s_and_b32 s6, s2, 0x7fc0
	v_or_b32_e32 v51, s6, v0
	v_cmp_lt_i32_e32 vcc, -1, v4
	v_lshl_add_u64 v[12:13], v[4:5], 2, s[22:23]
	v_mul_u32_u24_e32 v4, 0x1108, v51
	s_and_b64 s[2:3], vcc, s[36:37]
	v_mov_b32_e32 v29, 0
	v_lshlrev_b32_e32 v4, 2, v4
	v_mov_b32_e32 v28, 0
	s_and_saveexec_b64 s[38:39], s[2:3]
	s_cbranch_execz .LBB0_175
	v_lshl_add_u64 v[10:11], v[12:13], 0, v[4:5]
	global_load_dword v28, v[10:11], off nt
.LBB0_175:
	s_or_b64 exec, exec, s[38:39]
	s_and_saveexec_b64 s[38:39], s[2:3]
	s_cbranch_execz .LBB0_177
	v_lshl_add_u64 v[10:11], v[12:13], 0, v[4:5]
	v_add_co_u32_e32 v10, vcc, 0x8000, v10
	s_nop 1
	v_addc_co_u32_e32 v11, vcc, 0, v11, vcc
	global_load_dword v29, v[10:11], off offset:2112 nt
.LBB0_177:
	s_or_b64 exec, exec, s[38:39]
	v_mov_b32_e32 v10, 0
	v_mov_b32_e32 v11, 0
	s_and_saveexec_b64 s[38:39], s[2:3]
	s_cbranch_execz .LBB0_179
	v_lshl_add_u64 v[14:15], v[12:13], 0, v[4:5]
	v_add_co_u32_e32 v14, vcc, 0x11000, v14
	s_nop 1
	v_addc_co_u32_e32 v15, vcc, 0, v15, vcc
	global_load_dword v11, v[14:15], off offset:128 nt
.LBB0_179:
	s_or_b64 exec, exec, s[38:39]
	s_and_saveexec_b64 s[38:39], s[2:3]
	s_cbranch_execz .LBB0_181
	v_lshl_add_u64 v[14:15], v[12:13], 0, v[4:5]
	v_add_co_u32_e32 v14, vcc, 0x19000, v14
	s_nop 1
	v_addc_co_u32_e32 v15, vcc, 0, v15, vcc
	global_load_dword v10, v[14:15], off offset:2240 nt
.LBB0_181:
	s_or_b64 exec, exec, s[38:39]
	v_mov_b32_e32 v49, 0
	v_mov_b32_e32 v50, 0
	s_and_saveexec_b64 s[38:39], s[2:3]
	s_cbranch_execz .LBB0_183
	v_lshl_add_u64 v[14:15], v[12:13], 0, v[4:5]
	v_add_co_u32_e32 v14, vcc, 0x22000, v14
	s_nop 1
	v_addc_co_u32_e32 v15, vcc, 0, v15, vcc
	global_load_dword v50, v[14:15], off offset:256 nt
.LBB0_183:
	s_or_b64 exec, exec, s[38:39]
	s_and_saveexec_b64 s[38:39], s[2:3]
	s_cbranch_execz .LBB0_185
	v_lshl_add_u64 v[14:15], v[12:13], 0, v[4:5]
	v_add_co_u32_e32 v14, vcc, 0x2a000, v14
	s_nop 1
	v_addc_co_u32_e32 v15, vcc, 0, v15, vcc
	global_load_dword v49, v[14:15], off offset:2368 nt
.LBB0_185:
	s_or_b64 exec, exec, s[38:39]
	v_mov_b32_e32 v14, 0
	v_mov_b32_e32 v15, 0
	s_and_saveexec_b64 s[38:39], s[2:3]
	s_cbranch_execz .LBB0_187
	v_lshl_add_u64 v[16:17], v[12:13], 0, v[4:5]
	v_add_co_u32_e32 v16, vcc, 0x33000, v16
	s_nop 1
	v_addc_co_u32_e32 v17, vcc, 0, v17, vcc
	global_load_dword v15, v[16:17], off offset:384 nt
.LBB0_187:
	s_or_b64 exec, exec, s[38:39]
	s_and_saveexec_b64 s[38:39], s[2:3]
	s_cbranch_execz .LBB0_189
	v_lshl_add_u64 v[16:17], v[12:13], 0, v[4:5]
	v_add_co_u32_e32 v16, vcc, 0x3b000, v16
	s_nop 1
	v_addc_co_u32_e32 v17, vcc, 0, v17, vcc
	global_load_dword v14, v[16:17], off offset:2496 nt
.LBB0_189:
	s_or_b64 exec, exec, s[38:39]
	v_mov_b32_e32 v52, 0
	v_mov_b32_e32 v53, 0
	s_and_saveexec_b64 s[38:39], s[2:3]
	s_cbranch_execz .LBB0_191
	v_lshl_add_u64 v[16:17], v[12:13], 0, v[4:5]
	v_add_co_u32_e32 v16, vcc, 0x44000, v16
	s_nop 1
	v_addc_co_u32_e32 v17, vcc, 0, v17, vcc
	global_load_dword v53, v[16:17], off offset:512 nt
.LBB0_191:
	s_or_b64 exec, exec, s[38:39]
	s_and_saveexec_b64 s[38:39], s[2:3]
	s_cbranch_execz .LBB0_193
	v_lshl_add_u64 v[16:17], v[12:13], 0, v[4:5]
	v_add_co_u32_e32 v16, vcc, 0x4c000, v16
	s_nop 1
	v_addc_co_u32_e32 v17, vcc, 0, v17, vcc
	global_load_dword v52, v[16:17], off offset:2624 nt
.LBB0_193:
	s_or_b64 exec, exec, s[38:39]
	v_mov_b32_e32 v16, 0
	v_mov_b32_e32 v17, 0
	s_and_saveexec_b64 s[38:39], s[2:3]
	s_cbranch_execz .LBB0_195
	v_lshl_add_u64 v[18:19], v[12:13], 0, v[4:5]
	v_add_co_u32_e32 v18, vcc, 0x55000, v18
	s_nop 1
	v_addc_co_u32_e32 v19, vcc, 0, v19, vcc
	global_load_dword v17, v[18:19], off offset:640 nt
.LBB0_195:
	s_or_b64 exec, exec, s[38:39]
	s_and_saveexec_b64 s[38:39], s[2:3]
	s_cbranch_execz .LBB0_197
	v_lshl_add_u64 v[18:19], v[12:13], 0, v[4:5]
	v_add_co_u32_e32 v18, vcc, 0x5d000, v18
	s_nop 1
	v_addc_co_u32_e32 v19, vcc, 0, v19, vcc
	global_load_dword v16, v[18:19], off offset:2752 nt
.LBB0_197:
	s_or_b64 exec, exec, s[38:39]
	v_mov_b32_e32 v54, 0
	v_mov_b32_e32 v55, 0
	s_and_saveexec_b64 s[38:39], s[2:3]
	s_cbranch_execz .LBB0_199
	v_lshl_add_u64 v[18:19], v[12:13], 0, v[4:5]
	v_add_co_u32_e32 v18, vcc, 0x66000, v18
	s_nop 1
	v_addc_co_u32_e32 v19, vcc, 0, v19, vcc
	global_load_dword v55, v[18:19], off offset:768 nt
.LBB0_199:
	s_or_b64 exec, exec, s[38:39]
	s_and_saveexec_b64 s[38:39], s[2:3]
	s_cbranch_execz .LBB0_201
	v_lshl_add_u64 v[18:19], v[12:13], 0, v[4:5]
	v_add_co_u32_e32 v18, vcc, 0x6e000, v18
	s_nop 1
	v_addc_co_u32_e32 v19, vcc, 0, v19, vcc
	global_load_dword v54, v[18:19], off offset:2880 nt
.LBB0_201:
	s_or_b64 exec, exec, s[38:39]
	v_mov_b32_e32 v18, 0
	v_mov_b32_e32 v19, 0
	s_and_saveexec_b64 s[38:39], s[2:3]
	s_cbranch_execz .LBB0_203
	v_lshl_add_u64 v[20:21], v[12:13], 0, v[4:5]
	v_add_co_u32_e32 v20, vcc, 0x77000, v20
	s_nop 1
	v_addc_co_u32_e32 v21, vcc, 0, v21, vcc
	global_load_dword v19, v[20:21], off offset:896 nt
.LBB0_203:
	s_or_b64 exec, exec, s[38:39]
	s_and_saveexec_b64 s[38:39], s[2:3]
	s_cbranch_execz .LBB0_205
	v_lshl_add_u64 v[20:21], v[12:13], 0, v[4:5]
	v_add_co_u32_e32 v20, vcc, 0x7f000, v20
	s_nop 1
	v_addc_co_u32_e32 v21, vcc, 0, v21, vcc
	global_load_dword v18, v[20:21], off offset:3008 nt
; #define LAS __attribute__((address_space(3)))
; __device__ __forceinline__ void transpose_item(const float* colp, int N, const float* gk, bf16_t* WT, int ldw, int koff, int k0, int n0, LAS float* scr, int lane) {
;     float v[32];
; #pragma unroll
;     for (int i = 0; i < 32; ++i) { const int kk = 2 * i + (lane >> 5); v[i] = colp ? colp[(size_t)(k0 + kk) * N] : 0.f; }
; __device__ __forceinline__ void p0_prologue(const Args& a, LAS unsigned char* lds, int gw, int NGW, int wave, int lane) {
;     ...
;         r -= 2 * I_D;
;         if (r < I_IN) {
;             const int nblk = NIN / 32, kb = r / nblk, nb = r % nblk, n = nb * 32 + (lane & 31);
;             int src = -1;
;             if (n < 1536) src = n; else if (n < 2304) src = n + 8;
;             else if (n < 4352) { const int t = n - 2304; src = (((t >> 7) & 1) ? 3336 : 2312) + 128 * (t >> 8) + (t & 127); }
;             else if (n < 4360) src = n - 4352 + 1536;
;             transpose_item(src >= 0 ? a.win + src : nullptr, WIN_SRC, a.gmix, (bf16_t*)(ws + WS_WIN), DM, 0, kb * 64, nb * 32, scr, lane);
.LBB0_205:
	s_or_b64 exec, exec, s[38:39]
	v_mov_b32_e32 v56, 0
	v_mov_b32_e32 v57, 0
	s_and_saveexec_b64 s[38:39], s[2:3]
	s_cbranch_execz .LBB0_207
	v_lshl_add_u64 v[20:21], v[12:13], 0, v[4:5]
	v_add_co_u32_e32 v20, vcc, 0x88000, v20
	s_nop 1
	v_addc_co_u32_e32 v21, vcc, 0, v21, vcc
	global_load_dword v57, v[20:21], off offset:1024 nt
.LBB0_207:
	s_or_b64 exec, exec, s[38:39]
	s_and_saveexec_b64 s[38:39], s[2:3]
	s_cbranch_execz .LBB0_209
	v_lshl_add_u64 v[20:21], v[12:13], 0, v[4:5]
	v_add_co_u32_e32 v20, vcc, 0x90000, v20
	s_nop 1
	v_addc_co_u32_e32 v21, vcc, 0, v21, vcc
	global_load_dword v56, v[20:21], off offset:3136 nt
.LBB0_209:
	s_or_b64 exec, exec, s[38:39]
	v_mov_b32_e32 v20, 0
	v_mov_b32_e32 v21, 0
	s_and_saveexec_b64 s[38:39], s[2:3]
	s_cbranch_execz .LBB0_211
	v_lshl_add_u64 v[22:23], v[12:13], 0, v[4:5]
	v_add_co_u32_e32 v22, vcc, 0x99000, v22
	s_nop 1
	v_addc_co_u32_e32 v23, vcc, 0, v23, vcc
	global_load_dword v21, v[22:23], off offset:1152 nt
.LBB0_211:
	s_or_b64 exec, exec, s[38:39]
	s_and_saveexec_b64 s[38:39], s[2:3]
	s_cbranch_execz .LBB0_213
	v_lshl_add_u64 v[22:23], v[12:13], 0, v[4:5]
	v_add_co_u32_e32 v22, vcc, 0xa1000, v22
	s_nop 1
	v_addc_co_u32_e32 v23, vcc, 0, v23, vcc
	global_load_dword v20, v[22:23], off offset:3264 nt
.LBB0_213:
	s_or_b64 exec, exec, s[38:39]
	v_mov_b32_e32 v58, 0
	v_mov_b32_e32 v59, 0
	s_and_saveexec_b64 s[38:39], s[2:3]
	s_cbranch_execz .LBB0_215
	v_lshl_add_u64 v[22:23], v[12:13], 0, v[4:5]
	v_add_co_u32_e32 v22, vcc, 0xaa000, v22
	s_nop 1
	v_addc_co_u32_e32 v23, vcc, 0, v23, vcc
	global_load_dword v59, v[22:23], off offset:1280 nt
.LBB0_215:
	s_or_b64 exec, exec, s[38:39]
	s_and_saveexec_b64 s[38:39], s[2:3]
	s_cbranch_execz .LBB0_217
	v_lshl_add_u64 v[22:23], v[12:13], 0, v[4:5]
	v_add_co_u32_e32 v22, vcc, 0xb2000, v22
	s_nop 1
	v_addc_co_u32_e32 v23, vcc, 0, v23, vcc
	global_load_dword v58, v[22:23], off offset:3392 nt
.LBB0_217:
	s_or_b64 exec, exec, s[38:39]
	v_mov_b32_e32 v22, 0
	v_mov_b32_e32 v23, 0
	s_and_saveexec_b64 s[38:39], s[2:3]
	s_cbranch_execz .LBB0_219
	v_lshl_add_u64 v[24:25], v[12:13], 0, v[4:5]
	v_add_co_u32_e32 v24, vcc, 0xbb000, v24
	s_nop 1
	v_addc_co_u32_e32 v25, vcc, 0, v25, vcc
	global_load_dword v23, v[24:25], off offset:1408 nt
.LBB0_219:
	s_or_b64 exec, exec, s[38:39]
	s_and_saveexec_b64 s[38:39], s[2:3]
	s_cbranch_execz .LBB0_221
	v_lshl_add_u64 v[24:25], v[12:13], 0, v[4:5]
	v_add_co_u32_e32 v24, vcc, 0xc3000, v24
	s_nop 1
	v_addc_co_u32_e32 v25, vcc, 0, v25, vcc
	global_load_dword v22, v[24:25], off offset:3520 nt
.LBB0_221:
	s_or_b64 exec, exec, s[38:39]
	v_mov_b32_e32 v60, 0
	v_mov_b32_e32 v61, 0
	s_and_saveexec_b64 s[38:39], s[2:3]
	s_cbranch_execz .LBB0_223
	v_lshl_add_u64 v[24:25], v[12:13], 0, v[4:5]
	v_add_co_u32_e32 v24, vcc, 0xcc000, v24
	s_nop 1
	v_addc_co_u32_e32 v25, vcc, 0, v25, vcc
	global_load_dword v61, v[24:25], off offset:1536 nt
.LBB0_223:
	s_or_b64 exec, exec, s[38:39]
	s_and_saveexec_b64 s[38:39], s[2:3]
	s_cbranch_execz .LBB0_225
	v_lshl_add_u64 v[24:25], v[12:13], 0, v[4:5]
	v_add_co_u32_e32 v24, vcc, 0xd4000, v24
	s_nop 1
	v_addc_co_u32_e32 v25, vcc, 0, v25, vcc
	global_load_dword v60, v[24:25], off offset:3648 nt
.LBB0_225:
	s_or_b64 exec, exec, s[38:39]
	v_mov_b32_e32 v24, 0
	v_mov_b32_e32 v25, 0
	s_and_saveexec_b64 s[38:39], s[2:3]
	s_cbranch_execz .LBB0_227
	v_lshl_add_u64 v[26:27], v[12:13], 0, v[4:5]
	v_add_co_u32_e32 v26, vcc, 0xdd000, v26
	s_nop 1
	v_addc_co_u32_e32 v27, vcc, 0, v27, vcc
	global_load_dword v25, v[26:27], off offset:1664 nt
.LBB0_227:
	s_or_b64 exec, exec, s[38:39]
	s_and_saveexec_b64 s[38:39], s[2:3]
	s_cbranch_execz .LBB0_229
	v_lshl_add_u64 v[26:27], v[12:13], 0, v[4:5]
	v_add_co_u32_e32 v26, vcc, 0xe5000, v26
	s_nop 1
	v_addc_co_u32_e32 v27, vcc, 0, v27, vcc
	global_load_dword v24, v[26:27], off offset:3776 nt
.LBB0_229:
	s_or_b64 exec, exec, s[38:39]
	v_mov_b32_e32 v62, 0
	v_mov_b32_e32 v63, 0
	s_and_saveexec_b64 s[38:39], s[2:3]
	s_cbranch_execz .LBB0_231
	v_lshl_add_u64 v[26:27], v[12:13], 0, v[4:5]
	v_add_co_u32_e32 v26, vcc, 0xee000, v26
	s_nop 1
	v_addc_co_u32_e32 v27, vcc, 0, v27, vcc
	global_load_dword v63, v[26:27], off offset:1792 nt
.LBB0_231:
	s_or_b64 exec, exec, s[38:39]
	s_and_saveexec_b64 s[38:39], s[2:3]
	s_cbranch_execz .LBB0_233
	v_lshl_add_u64 v[26:27], v[12:13], 0, v[4:5]
	v_add_co_u32_e32 v26, vcc, 0xf6000, v26
	s_nop 1
	v_addc_co_u32_e32 v27, vcc, 0, v27, vcc
	global_load_dword v62, v[26:27], off offset:3904 nt
.LBB0_233:
	s_or_b64 exec, exec, s[38:39]
	v_mov_b32_e32 v26, 0
	v_mov_b32_e32 v27, 0
	s_and_saveexec_b64 s[38:39], s[2:3]
	s_cbranch_execz .LBB0_235
	v_lshl_add_u64 v[64:65], v[12:13], 0, v[4:5]
	v_add_co_u32_e32 v64, vcc, 0xff000, v64
	s_nop 1
	v_addc_co_u32_e32 v65, vcc, 0, v65, vcc
	global_load_dword v27, v[64:65], off offset:1920 nt
.LBB0_235:
	s_or_b64 exec, exec, s[38:39]
	s_and_saveexec_b64 s[38:39], s[2:3]
	s_cbranch_execz .LBB0_237
	v_lshl_add_u64 v[12:13], v[12:13], 0, v[4:5]
	v_add_co_u32_e32 v12, vcc, 0x107000, v12
	s_nop 1
	v_addc_co_u32_e32 v13, vcc, 0, v13, vcc
	global_load_dword v26, v[12:13], off offset:4032 nt

; #define LAS __attribute__((address_space(3)))
; __device__ __forceinline__ void transpose_item(const float* colp, int N, const float* gk, bf16_t* WT, int ldw, int koff, int k0, int n0, LAS float* scr, int lane) {
;     float v[32];
; #pragma unroll
;     for (int i = 0; i < 32; ++i) { const int kk = 2 * i + (lane >> 5); v[i] = colp ? colp[(size_t)(k0 + kk) * N] : 0.f; }
; __device__ __forceinline__ void p0_prologue(const Args& a, LAS unsigned char* lds, int gw, int NGW, int wave, int lane) {
;     ...
;         r -= 2 * I_GU;
;         if (r < 2 * I_D) {
;             const bool second = r >= I_D; if (second) r -= I_D;
;             const int nblk = DM / 32, kb = r / nblk, nb = r % nblk, n = nb * 32 + (lane & 31);
;             transpose_item((second ? a.w2d : a.w1d) + n, DM, nullptr, (bf16_t*)(ws + (second ? WS_W2D : WS_W1D)), DFF, 0, kb * 64, nb * 32, scr, lane);
;             continue;
.LBB0_263:
	s_andn2_b64 vcc, exec, s[2:3]
	s_cbranch_vccnz .LBB0_329
	s_cmpk_gt_u32 s87, 0x1b7f
	s_cselect_b64 s[38:39], -1, 0
	s_and_b64 s[2:3], s[38:39], exec
	s_cselect_b32 s2, s83, 0xffffea00
	s_add_i32 s40, s2, s87
	s_lshl_b32 s2, s40, 5
	s_and_b32 s6, s2, 0x3e0
	v_readlane_b32 s48, v245, 1
	s_and_b64 s[2:3], s[38:39], exec
	v_readlane_b32 s52, v245, 5
	v_readlane_b32 s53, v245, 6
	s_cselect_b32 s3, s53, s19
	s_cselect_b32 s2, s52, s18
	s_lshl_b32 s40, s40, 1
	v_or_b32_e32 v4, s6, v3
	s_and_b32 s42, s40, 0x7fffffc0
	v_lshlrev_b32_e32 v4, 2, v4
	s_cmp_lg_u64 s[2:3], 0
	v_lshl_add_u64 v[10:11], s[2:3], 0, v[4:5]
	s_cselect_b64 s[40:41], -1, 0
	s_cmp_eq_u64 s[2:3], 0
	v_or_b32_e32 v4, s42, v0
	v_mov_b32_e32 v13, 0
	v_mov_b32_e32 v12, 0
	v_readlane_b32 s49, v245, 2
	v_readlane_b32 s50, v245, 3
	v_readlane_b32 s51, v245, 4
	v_readlane_b32 s54, v245, 7
	v_readlane_b32 s55, v245, 8
	s_cbranch_scc1 .LBB0_266
	v_lshlrev_b64 v[14:15], 12, v[4:5]
	v_lshl_add_u64 v[14:15], v[10:11], 0, v[14:15]
	global_load_dword v12, v[14:15], off nt

; #define LAS __attribute__((address_space(3)))
; __device__ __forceinline__ void transpose_item(const float* colp, int N, const float* gk, bf16_t* WT, int ldw, int koff, int k0, int n0, LAS float* scr, int lane) {
;     float v[32];
; #pragma unroll
;     for (int i = 0; i < 32; ++i) { const int kk = 2 * i + (lane >> 5); v[i] = colp ? colp[(size_t)(k0 + kk) * N] : 0.f; }
; __device__ __forceinline__ void p0_prologue(const Args& a, LAS unsigned char* lds, int gw, int NGW, int wave, int lane) {
;     ...
;         int r = it;
;         if (r < 2 * I_GU) {
;             const bool second = r >= I_GU; if (second) r -= I_GU;
;             const int nblk = NGU / 32, kb = r / nblk, nb = r % nblk, n = nb * 32 + (lane & 31);
;             const float* wg = second ? a.w2g : a.w1g; const float* wu = second ? a.w2u : a.w1u;
;             const float* colp = (((n >> 7) & 1) ? wu : wg) + 128 * (n >> 8) + (n & 127);
;             transpose_item(colp, DFF, second ? a.g2 : a.g1, (bf16_t*)(ws + (second ? WS_W2GU : WS_W1GU)), DM, 0, kb * 64, nb * 32, scr, lane);
.LBB0_330:
	s_andn2_b64 vcc, exec, s[2:3]
	s_cbranch_vccnz .LBB0_26
	s_add_i32 s6, s87, 0xfffff500
	s_cmpk_gt_i32 s87, 0xaff
	s_cselect_b64 s[38:39], -1, 0
	s_and_b64 s[2:3], s[38:39], exec
	s_cselect_b32 s2, s6, s87
	v_readlane_b32 s48, v245, 1
	s_mul_hi_i32 s3, s2, 0x2e8ba2e9
	v_readlane_b32 s49, v245, 2
	v_readlane_b32 s50, v245, 3
	v_readlane_b32 s51, v245, 4
	s_cselect_b32 s40, s48, s14
	s_cselect_b32 s41, s49, s15
	s_cselect_b32 s42, s50, s16
	s_cselect_b32 s43, s51, s17
	s_lshr_b32 s6, s3, 31
	s_ashr_i32 s3, s3, 5
	s_add_i32 s44, s3, s6
	s_mul_i32 s3, s44, 0xb0
	s_sub_i32 s45, s2, s3
	s_lshl_b32 s6, s45, 5
	s_bitcmp0_b32 s45, 2
	s_cselect_b32 s3, s41, s43
	s_cselect_b32 s2, s40, s42
	s_lshl_b32 s40, s45, 4
	s_and_b32 s40, s40, 0xffffff80
	s_ashr_i32 s41, s40, 31
	s_lshl_b64 s[40:41], s[40:41], 2
	s_add_u32 s40, s2, s40
	s_addc_u32 s41, s3, s41
	s_and_b32 s42, s6, 0x60
	v_or_b32_e32 v4, s42, v3
	v_lshlrev_b32_e32 v4, 2, v4
	v_lshl_add_u64 v[28:29], s[40:41], 0, v[4:5]
	s_lshl_b32 s40, s44, 6
	s_cmp_lg_u64 s[2:3], 0
	s_cselect_b64 s[42:43], -1, 0
	s_cmp_eq_u64 s[2:3], 0
	v_or_b32_e32 v26, s40, v0
	v_mov_b32_e32 v62, 0
	v_mov_b32_e32 v63, 0
	v_readlane_b32 s52, v245, 5
	v_readlane_b32 s53, v245, 6
	v_readlane_b32 s54, v245, 7
	v_readlane_b32 s55, v245, 8
	s_cbranch_scc1 .LBB0_333
	v_mad_i64_i32 v[10:11], s[2:3], v26, s85, v[28:29]
	global_load_dword v63, v[10:11], off nt
.LBB0_333:
	v_cndmask_b32_e64 v4, 0, 1, s[42:43]
	v_cmp_ne_u32_e64 s[2:3], 1, v4
	s_andn2_b64 vcc, exec, s[42:43]
	s_cbranch_vccnz .LBB0_335
	v_or_b32_e32 v4, 2, v26
	v_mad_i64_i32 v[10:11], s[42:43], v4, s85, v[28:29]
	global_load_dword v62, v[10:11], off nt
.LBB0_335:
	v_mov_b32_e32 v24, 0
	s_and_b64 vcc, exec, s[2:3]
	v_mov_b32_e32 v25, 0
	s_cbranch_vccnz .LBB0_337
	v_or_b32_e32 v4, 4, v26
	v_mad_i64_i32 v[10:11], s[42:43], v4, s85, v[28:29]
	global_load_dword v25, v[10:11], off nt
.LBB0_337:
	s_and_b64 vcc, exec, s[2:3]
	s_cbranch_vccnz .LBB0_339
	v_or_b32_e32 v4, 6, v26
	v_mad_i64_i32 v[10:11], s[42:43], v4, s85, v[28:29]
	global_load_dword v24, v[10:11], off nt
.LBB0_339:
	v_mov_b32_e32 v60, 0
	s_and_b64 vcc, exec, s[2:3]
	v_mov_b32_e32 v61, 0
	s_cbranch_vccnz .LBB0_341
	v_or_b32_e32 v4, 8, v26
	v_mad_i64_i32 v[10:11], s[42:43], v4, s85, v[28:29]
	global_load_dword v61, v[10:11], off nt
.LBB0_341:
	s_and_b64 vcc, exec, s[2:3]
	s_cbranch_vccnz .LBB0_343
	v_or_b32_e32 v4, 10, v26
	v_mad_i64_i32 v[10:11], s[42:43], v4, s85, v[28:29]
	global_load_dword v60, v[10:11], off nt
.LBB0_343:
	v_mov_b32_e32 v22, 0
	s_and_b64 vcc, exec, s[2:3]
	v_mov_b32_e32 v23, 0
	s_cbranch_vccnz .LBB0_345
	v_or_b32_e32 v4, 12, v26
	v_mad_i64_i32 v[10:11], s[42:43], v4, s85, v[28:29]
	global_load_dword v23, v[10:11], off nt
.LBB0_345:
	s_and_b64 vcc, exec, s[2:3]
	s_cbranch_vccnz .LBB0_347
	v_or_b32_e32 v4, 14, v26
	v_mad_i64_i32 v[10:11], s[42:43], v4, s85, v[28:29]
	global_load_dword v22, v[10:11], off nt
.LBB0_347:
	v_mov_b32_e32 v58, 0
	s_and_b64 vcc, exec, s[2:3]
	v_mov_b32_e32 v59, 0
	s_cbranch_vccnz .LBB0_349
	v_or_b32_e32 v4, 16, v26
	v_mad_i64_i32 v[10:11], s[42:43], v4, s85, v[28:29]
	global_load_dword v59, v[10:11], off nt
.LBB0_349:
	s_and_b64 vcc, exec, s[2:3]
	s_cbranch_vccnz .LBB0_351
	v_or_b32_e32 v4, 18, v26
	v_mad_i64_i32 v[10:11], s[42:43], v4, s85, v[28:29]
	global_load_dword v58, v[10:11], off nt
.LBB0_351:
	v_mov_b32_e32 v20, 0
	s_and_b64 vcc, exec, s[2:3]
	v_mov_b32_e32 v21, 0
	s_cbranch_vccnz .LBB0_353
	v_or_b32_e32 v4, 20, v26
	v_mad_i64_i32 v[10:11], s[42:43], v4, s85, v[28:29]
	global_load_dword v21, v[10:11], off nt
.LBB0_353:
	s_and_b64 vcc, exec, s[2:3]
	s_cbranch_vccnz .LBB0_355
	v_or_b32_e32 v4, 22, v26
	v_mad_i64_i32 v[10:11], s[42:43], v4, s85, v[28:29]
	global_load_dword v20, v[10:11], off nt
.LBB0_355:
	v_mov_b32_e32 v56, 0
	s_and_b64 vcc, exec, s[2:3]
	v_mov_b32_e32 v57, 0
	s_cbranch_vccnz .LBB0_357
	v_or_b32_e32 v4, 24, v26
	v_mad_i64_i32 v[10:11], s[42:43], v4, s85, v[28:29]
	global_load_dword v57, v[10:11], off nt
.LBB0_357:
	s_and_b64 vcc, exec, s[2:3]
	s_cbranch_vccnz .LBB0_359
	v_or_b32_e32 v4, 26, v26
	v_mad_i64_i32 v[10:11], s[42:43], v4, s85, v[28:29]
	global_load_dword v56, v[10:11], off nt
.LBB0_359:
	v_mov_b32_e32 v18, 0
	s_and_b64 vcc, exec, s[2:3]
	v_mov_b32_e32 v19, 0
	s_cbranch_vccnz .LBB0_361
	v_or_b32_e32 v4, 28, v26
	v_mad_i64_i32 v[10:11], s[42:43], v4, s85, v[28:29]
	global_load_dword v19, v[10:11], off nt
; #define LAS __attribute__((address_space(3)))
; __device__ __forceinline__ void transpose_item(const float* colp, int N, const float* gk, bf16_t* WT, int ldw, int koff, int k0, int n0, LAS float* scr, int lane) {
;     float v[32];
; #pragma unroll
;     for (int i = 0; i < 32; ++i) { const int kk = 2 * i + (lane >> 5); v[i] = colp ? colp[(size_t)(k0 + kk) * N] : 0.f; }
; #pragma unroll
;     for (int i = 0; i < 32; ++i) { const int kk = 2 * i + (lane >> 5); scr[kk * 33 + (lane & 31)] = gk ? v[i] * gk[k0 + kk] : v[i]; }
; __device__ __forceinline__ void p0_prologue(const Args& a, LAS unsigned char* lds, int gw, int NGW, int wave, int lane) {
;     ...
;         int r = it;
;         if (r < 2 * I_GU) {
;             const bool second = r >= I_GU; if (second) r -= I_GU;
;             const int nblk = NGU / 32, kb = r / nblk, nb = r % nblk, n = nb * 32 + (lane & 31);
;             const float* wg = second ? a.w2g : a.w1g; const float* wu = second ? a.w2u : a.w1u;
;             const float* colp = (((n >> 7) & 1) ? wu : wg) + 128 * (n >> 8) + (n & 127);
;             transpose_item(colp, DFF, second ? a.g2 : a.g1, (bf16_t*)(ws + (second ? WS_W2GU : WS_W1GU)), DM, 0, kb * 64, nb * 32, scr, lane);
.LBB0_361:
	s_and_b64 vcc, exec, s[2:3]
	s_cbranch_vccnz .LBB0_363
	v_or_b32_e32 v4, 30, v26
	v_mad_i64_i32 v[10:11], s[42:43], v4, s85, v[28:29]
	global_load_dword v18, v[10:11], off nt
.LBB0_363:
	v_mov_b32_e32 v54, 0
	s_and_b64 vcc, exec, s[2:3]
	v_mov_b32_e32 v55, 0
	s_cbranch_vccnz .LBB0_365
	v_or_b32_e32 v4, 32, v26
	v_mad_i64_i32 v[10:11], s[42:43], v4, s85, v[28:29]
	global_load_dword v55, v[10:11], off nt
.LBB0_365:
	s_and_b64 vcc, exec, s[2:3]
	s_cbranch_vccnz .LBB0_367
	v_or_b32_e32 v4, 34, v26
	v_mad_i64_i32 v[10:11], s[42:43], v4, s85, v[28:29]
	global_load_dword v54, v[10:11], off nt
.LBB0_367:
	v_mov_b32_e32 v16, 0
	s_and_b64 vcc, exec, s[2:3]
	v_mov_b32_e32 v17, 0
	s_cbranch_vccnz .LBB0_369
	v_or_b32_e32 v4, 36, v26
	v_mad_i64_i32 v[10:11], s[42:43], v4, s85, v[28:29]
	global_load_dword v17, v[10:11], off nt
.LBB0_369:
	s_and_b64 vcc, exec, s[2:3]
	s_cbranch_vccnz .LBB0_371
	v_or_b32_e32 v4, 38, v26
	v_mad_i64_i32 v[10:11], s[42:43], v4, s85, v[28:29]
	global_load_dword v16, v[10:11], off nt
.LBB0_371:
	v_mov_b32_e32 v52, 0
	s_and_b64 vcc, exec, s[2:3]
	v_mov_b32_e32 v53, 0
	s_cbranch_vccnz .LBB0_373
	v_or_b32_e32 v4, 40, v26
	v_mad_i64_i32 v[10:11], s[42:43], v4, s85, v[28:29]
	global_load_dword v53, v[10:11], off nt
.LBB0_373:
	s_and_b64 vcc, exec, s[2:3]
	s_cbranch_vccnz .LBB0_375
	v_or_b32_e32 v4, 42, v26
	v_mad_i64_i32 v[10:11], s[42:43], v4, s85, v[28:29]
	global_load_dword v52, v[10:11], off nt
.LBB0_375:
	v_mov_b32_e32 v14, 0
	s_and_b64 vcc, exec, s[2:3]
	v_mov_b32_e32 v15, 0
	s_cbranch_vccnz .LBB0_377
	v_or_b32_e32 v4, 44, v26
	v_mad_i64_i32 v[10:11], s[42:43], v4, s85, v[28:29]
	global_load_dword v15, v[10:11], off nt
.LBB0_377:
	s_and_b64 vcc, exec, s[2:3]
	s_cbranch_vccnz .LBB0_379
	v_or_b32_e32 v4, 46, v26
	v_mad_i64_i32 v[10:11], s[42:43], v4, s85, v[28:29]
	global_load_dword v14, v[10:11], off nt
.LBB0_379:
	v_mov_b32_e32 v50, 0
	s_and_b64 vcc, exec, s[2:3]
	v_mov_b32_e32 v51, 0
	s_cbranch_vccnz .LBB0_381
	v_or_b32_e32 v4, 48, v26
	v_mad_i64_i32 v[10:11], s[42:43], v4, s85, v[28:29]
	global_load_dword v51, v[10:11], off nt
.LBB0_381:
	s_and_b64 vcc, exec, s[2:3]
	s_cbranch_vccnz .LBB0_383
	v_or_b32_e32 v4, 50, v26
	v_mad_i64_i32 v[10:11], s[42:43], v4, s85, v[28:29]
	global_load_dword v50, v[10:11], off nt
.LBB0_383:
	v_mov_b32_e32 v12, 0
	s_and_b64 vcc, exec, s[2:3]
	v_mov_b32_e32 v13, 0
	s_cbranch_vccnz .LBB0_385
	v_or_b32_e32 v4, 52, v26
	v_mad_i64_i32 v[10:11], s[42:43], v4, s85, v[28:29]
	global_load_dword v13, v[10:11], off nt
.LBB0_385:
	s_and_b64 vcc, exec, s[2:3]
	s_cbranch_vccnz .LBB0_387
	v_or_b32_e32 v4, 54, v26
	v_mad_i64_i32 v[10:11], s[42:43], v4, s85, v[28:29]
	global_load_dword v12, v[10:11], off nt
.LBB0_387:
	v_mov_b32_e32 v4, 0
	s_and_b64 vcc, exec, s[2:3]
	v_mov_b32_e32 v49, 0
	s_cbranch_vccnz .LBB0_389
	v_or_b32_e32 v10, 56, v26
	v_mad_i64_i32 v[10:11], s[42:43], v10, s85, v[28:29]
	global_load_dword v49, v[10:11], off nt
.LBB0_389:
	s_and_b64 vcc, exec, s[2:3]
	s_cbranch_vccnz .LBB0_391
	v_or_b32_e32 v4, 58, v26
	v_mad_i64_i32 v[10:11], s[42:43], v4, s85, v[28:29]
	global_load_dword v4, v[10:11], off nt
.LBB0_391:
	v_mov_b32_e32 v10, 0
	s_and_b64 vcc, exec, s[2:3]
	v_mov_b32_e32 v11, 0
	s_cbranch_vccnz .LBB0_393
	v_or_b32_e32 v11, 60, v26
	v_mad_i64_i32 v[64:65], s[42:43], v11, s85, v[28:29]
	global_load_dword v11, v[64:65], off nt
.LBB0_393:
	s_and_b64 vcc, exec, s[2:3]
	s_cbranch_vccnz .LBB0_395
	v_or_b32_e32 v10, 62, v26
	v_mad_i64_i32 v[28:29], s[2:3], v10, s85, v[28:29]
	global_load_dword v10, v[28:29], off nt
.LBB0_395:
	s_and_b64 s[2:3], s[38:39], exec
	s_cselect_b32 s43, s71, s13
	s_cselect_b32 s42, s70, s12
	s_cmp_lg_u64 s[42:43], 0
	s_cselect_b64 s[44:45], -1, 0
	s_cmp_eq_u64 s[42:43], 0
	v_add_u32_e32 v28, v30, v37
	s_cbranch_scc1 .LBB0_418
	v_ashrrev_i32_e32 v27, 31, v26
	s_ashr_i32 s41, s40, 31
	v_lshl_add_u64 v[26:27], v[26:27], 2, s[42:43]
	v_lshl_add_u64 v[64:65], s[40:41], 0, v[0:1]
	v_lshl_add_u64 v[64:65], v[64:65], 2, s[42:43]
	global_load_dword v29, v[26:27], off nt
	global_load_dword v66, v[64:65], off offset:8 nt
	s_nop 0
	global_load_dword v27, v[64:65], off offset:16 nt
	global_load_dword v26, v[64:65], off offset:24 nt
	s_waitcnt vmcnt(3)
	v_mul_f32_e32 v29, v63, v29
	s_waitcnt vmcnt(2)
	v_mul_f32_e32 v64, v62, v66
	ds_write_b32 v31, v29
	s_waitcnt vmcnt(0)
	v_pk_mul_f32 v[26:27], v[24:25], v[26:27]
	ds_write_b32 v28, v64
	s_cbranch_execnz .LBB0_398

; __device__ __forceinline__ void transpose_item(const float* colp, int N, const float* gk, bf16_t* WT, int ldw, int koff, int k0, int n0, LAS float* scr, int lane) {
;     ...
;     for (int i = 0; i < 32; ++i) { const int kk = 2 * i + (lane >> 5); v[i] = colp ? colp[(size_t)(k0 + kk) * N] : 0.f; }
; #pragma unroll
;     for (int i = 0; i < 32; ++i) { const int kk = 2 * i + (lane >> 5); scr[kk * 33 + (lane & 31)] = gk ? v[i] * gk[k0 + kk] : v[i]; }
.LBB0_398:
	s_waitcnt vmcnt(0)
	v_add_u32_e32 v24, v30, v38
	ds_write2_b32 v24, v27, v26 offset1:66
	v_cndmask_b32_e64 v24, 0, 1, s[44:45]
	v_cmp_ne_u32_e64 s[2:3], 1, v24
	s_andn2_b64 vcc, exec, s[44:45]
	v_add_u32_e32 v26, v30, v39
	s_cbranch_vccnz .LBB0_419
	s_ashr_i32 s41, s40, 31
	v_lshl_add_u64 v[24:25], s[40:41], 0, v[0:1]
	v_lshl_add_u64 v[24:25], v[24:25], 2, s[42:43]
	global_load_dword v27, v[24:25], off offset:32 nt
	global_load_dword v62, v[24:25], off offset:40 nt
	global_load_dword v29, v[24:25], off offset:48 nt
	global_load_dword v28, v[24:25], off offset:56 nt
	s_waitcnt vmcnt(3)
	v_mul_f32_e32 v27, v61, v27
	s_waitcnt vmcnt(2)
	v_mul_f32_e32 v62, v60, v62
	ds_write2_b32 v26, v27, v62 offset1:66
	s_waitcnt vmcnt(0)
	v_pk_mul_f32 v[24:25], v[22:23], v[28:29]
	s_cbranch_execnz .LBB0_401

; __device__ __forceinline__ void transpose_item(const float* colp, int N, const float* gk, bf16_t* WT, int ldw, int koff, int k0, int n0, LAS float* scr, int lane) {
;     ...
;     for (int i = 0; i < 32; ++i) { const int kk = 2 * i + (lane >> 5); v[i] = colp ? colp[(size_t)(k0 + kk) * N] : 0.f; }
; #pragma unroll
;     for (int i = 0; i < 32; ++i) { const int kk = 2 * i + (lane >> 5); scr[kk * 33 + (lane & 31)] = gk ? v[i] * gk[k0 + kk] : v[i]; }
.LBB0_401:
	v_add_u32_e32 v22, v30, v40
	ds_write2_b32 v22, v25, v24 offset1:66
	s_and_b64 vcc, exec, s[2:3]
	v_add_u32_e32 v24, v30, v41
	s_cbranch_vccnz .LBB0_420
	s_ashr_i32 s41, s40, 31
	v_lshl_add_u64 v[22:23], s[40:41], 0, v[0:1]
	v_lshl_add_u64 v[22:23], v[22:23], 2, s[42:43]
	global_load_dword v25, v[22:23], off offset:64 nt
	global_load_dword v28, v[22:23], off offset:72 nt
	global_load_dword v27, v[22:23], off offset:80 nt
	global_load_dword v26, v[22:23], off offset:88 nt
	s_waitcnt vmcnt(3)
	v_mul_f32_e32 v25, v59, v25
	s_waitcnt vmcnt(2)
	v_mul_f32_e32 v28, v58, v28
	ds_write2_b32 v24, v25, v28 offset1:66
	s_waitcnt vmcnt(0)
	v_pk_mul_f32 v[22:23], v[20:21], v[26:27]
	s_cbranch_execnz .LBB0_404

; __device__ __forceinline__ void transpose_item(const float* colp, int N, const float* gk, bf16_t* WT, int ldw, int koff, int k0, int n0, LAS float* scr, int lane) {
;     ...
;     for (int i = 0; i < 32; ++i) { const int kk = 2 * i + (lane >> 5); v[i] = colp ? colp[(size_t)(k0 + kk) * N] : 0.f; }
; #pragma unroll
;     for (int i = 0; i < 32; ++i) { const int kk = 2 * i + (lane >> 5); scr[kk * 33 + (lane & 31)] = gk ? v[i] * gk[k0 + kk] : v[i]; }
.LBB0_404:
	v_add_u32_e32 v20, v30, v42
	ds_write2_b32 v20, v23, v22 offset1:66
	s_and_b64 vcc, exec, s[2:3]
	v_add_u32_e32 v22, v30, v43
	s_cbranch_vccnz .LBB0_421
	s_ashr_i32 s41, s40, 31
	v_lshl_add_u64 v[20:21], s[40:41], 0, v[0:1]
	v_lshl_add_u64 v[20:21], v[20:21], 2, s[42:43]
	global_load_dword v23, v[20:21], off offset:96 nt
	global_load_dword v26, v[20:21], off offset:104 nt
	global_load_dword v25, v[20:21], off offset:112 nt
	global_load_dword v24, v[20:21], off offset:120 nt
	s_waitcnt vmcnt(3)
	v_mul_f32_e32 v23, v57, v23
	s_waitcnt vmcnt(2)
	v_mul_f32_e32 v26, v56, v26
	ds_write2_b32 v22, v23, v26 offset1:66
	s_waitcnt vmcnt(0)
	v_pk_mul_f32 v[20:21], v[18:19], v[24:25]
	s_cbranch_execnz .LBB0_407

; __device__ __forceinline__ void transpose_item(const float* colp, int N, const float* gk, bf16_t* WT, int ldw, int koff, int k0, int n0, LAS float* scr, int lane) {
;     ...
;     for (int i = 0; i < 32; ++i) { const int kk = 2 * i + (lane >> 5); v[i] = colp ? colp[(size_t)(k0 + kk) * N] : 0.f; }
; #pragma unroll
;     for (int i = 0; i < 32; ++i) { const int kk = 2 * i + (lane >> 5); scr[kk * 33 + (lane & 31)] = gk ? v[i] * gk[k0 + kk] : v[i]; }
.LBB0_407:
	v_add_u32_e32 v18, v30, v44
	ds_write2_b32 v18, v21, v20 offset1:66
	s_and_b64 vcc, exec, s[2:3]
	v_add_u32_e32 v20, v30, v45
	s_cbranch_vccnz .LBB0_422
	s_ashr_i32 s41, s40, 31
	v_lshl_add_u64 v[18:19], s[40:41], 0, v[0:1]
	v_lshl_add_u64 v[18:19], v[18:19], 2, s[42:43]
	global_load_dword v21, v[18:19], off offset:128 nt
	global_load_dword v24, v[18:19], off offset:136 nt
	global_load_dword v23, v[18:19], off offset:144 nt
	global_load_dword v22, v[18:19], off offset:152 nt
	s_waitcnt vmcnt(3)
	v_mul_f32_e32 v21, v55, v21
	s_waitcnt vmcnt(2)
	v_mul_f32_e32 v24, v54, v24
	ds_write2_b32 v20, v21, v24 offset1:66
	s_waitcnt vmcnt(0)
	v_pk_mul_f32 v[18:19], v[16:17], v[22:23]
	s_cbranch_execnz .LBB0_410

; __device__ __forceinline__ void transpose_item(const float* colp, int N, const float* gk, bf16_t* WT, int ldw, int koff, int k0, int n0, LAS float* scr, int lane) {
;     ...
;     for (int i = 0; i < 32; ++i) { const int kk = 2 * i + (lane >> 5); v[i] = colp ? colp[(size_t)(k0 + kk) * N] : 0.f; }
; #pragma unroll
;     for (int i = 0; i < 32; ++i) { const int kk = 2 * i + (lane >> 5); scr[kk * 33 + (lane & 31)] = gk ? v[i] * gk[k0 + kk] : v[i]; }
.LBB0_410:
	v_add_u32_e32 v16, v30, v46
	ds_write2_b32 v16, v19, v18 offset1:66
	s_and_b64 vcc, exec, s[2:3]
	v_add_u32_e32 v18, v30, v47
	s_cbranch_vccnz .LBB0_423
	s_ashr_i32 s41, s40, 31
	v_lshl_add_u64 v[16:17], s[40:41], 0, v[0:1]
	v_lshl_add_u64 v[16:17], v[16:17], 2, s[42:43]
	global_load_dword v19, v[16:17], off offset:160 nt
	global_load_dword v22, v[16:17], off offset:168 nt
	global_load_dword v21, v[16:17], off offset:176 nt
	global_load_dword v20, v[16:17], off offset:184 nt
	s_waitcnt vmcnt(3)
	v_mul_f32_e32 v19, v53, v19
	s_waitcnt vmcnt(2)
	v_mul_f32_e32 v22, v52, v22
	ds_write2_b32 v18, v19, v22 offset1:66
	s_waitcnt vmcnt(0)
	v_pk_mul_f32 v[16:17], v[14:15], v[20:21]
	s_cbranch_execnz .LBB0_413

; __device__ __forceinline__ void transpose_item(const float* colp, int N, const float* gk, bf16_t* WT, int ldw, int koff, int k0, int n0, LAS float* scr, int lane) {
;     ...
;     for (int i = 0; i < 32; ++i) { const int kk = 2 * i + (lane >> 5); v[i] = colp ? colp[(size_t)(k0 + kk) * N] : 0.f; }
; #pragma unroll
;     for (int i = 0; i < 32; ++i) { const int kk = 2 * i + (lane >> 5); scr[kk * 33 + (lane & 31)] = gk ? v[i] * gk[k0 + kk] : v[i]; }
.LBB0_413:
	ds_write2_b32 v18, v17, v16 offset0:132 offset1:198
	s_and_b64 vcc, exec, s[2:3]
	v_add_u32_e32 v16, 0x400, v18
	s_cbranch_vccnz .LBB0_424
	s_ashr_i32 s41, s40, 31
	v_lshl_add_u64 v[14:15], s[40:41], 0, v[0:1]
	v_lshl_add_u64 v[14:15], v[14:15], 2, s[42:43]
	global_load_dword v17, v[14:15], off offset:192 nt
	global_load_dword v19, v[14:15], off offset:200 nt
	global_load_dword v21, v[14:15], off offset:208 nt
	global_load_dword v20, v[14:15], off offset:216 nt
	s_waitcnt vmcnt(3)
	v_mul_f32_e32 v17, v51, v17
	s_waitcnt vmcnt(2)
	v_mul_f32_e32 v19, v50, v19
	ds_write2_b32 v16, v17, v19 offset0:8 offset1:74
	s_waitcnt vmcnt(0)
	v_pk_mul_f32 v[14:15], v[12:13], v[20:21]
	s_cbranch_execnz .LBB0_416

; __device__ __forceinline__ void transpose_item(const float* colp, int N, const float* gk, bf16_t* WT, int ldw, int koff, int k0, int n0, LAS float* scr, int lane) {
;     ...
;     for (int i = 0; i < 32; ++i) { const int kk = 2 * i + (lane >> 5); v[i] = colp ? colp[(size_t)(k0 + kk) * N] : 0.f; }
; #pragma unroll
;     for (int i = 0; i < 32; ++i) { const int kk = 2 * i + (lane >> 5); scr[kk * 33 + (lane & 31)] = gk ? v[i] * gk[k0 + kk] : v[i]; }
.LBB0_416:
	ds_write2_b32 v16, v15, v14 offset0:140 offset1:206
	s_and_b64 vcc, exec, s[2:3]
	v_add_u32_e32 v14, 0x800, v18
	s_cbranch_vccnz .LBB0_425
	s_ashr_i32 s41, s40, 31
	v_lshl_add_u64 v[12:13], s[40:41], 0, v[0:1]
	v_lshl_add_u64 v[12:13], v[12:13], 2, s[42:43]
	global_load_dword v15, v[12:13], off offset:224 nt
	global_load_dword v18, v[12:13], off offset:232 nt
	global_load_dword v17, v[12:13], off offset:240 nt
	global_load_dword v16, v[12:13], off offset:248 nt
	s_waitcnt vmcnt(3)
	v_mul_f32_e32 v15, v49, v15
	s_waitcnt vmcnt(2)
	v_mul_f32_e32 v18, v4, v18
	ds_write2_b32 v14, v15, v18 offset0:16 offset1:82
	s_waitcnt vmcnt(0)
	v_pk_mul_f32 v[12:13], v[10:11], v[16:17]
	s_cbranch_execnz .LBB0_25
	s_branch .LBB0_426

; __device__ __forceinline__ void p0_prologue(const Args& a, LAS unsigned char* lds, int gw, int NGW, int wave, int lane) {
;     ...
;     float* rope = (float*)(ws + WS_ROPE);
;     for (int idx = gw * 64 + lane; idx < M * 8; idx += NGW * 64) {
;         const int row = idx >> 3, i = idx & 7;
;         const float inv = i == 0 ? 1.0f : i == 1 ? 0.1939227432012558f : i == 2 ? 0.03760603070259094f : i == 3 ? 0.007292664609849453f : i == 4 ? 0.0014142135623842478f
;                         : i == 5 ? 0.00027424818836152554f : i == 6 ? 5.3182957344688475e-05f : 1.0313385246263351e-05f;
;         const float ang = (float)a.pos[row] * inv; float sn, cs; sincosf(ang, &sn, &cs);
;         rope[(size_t)row * 16 + i] = cs; rope[(size_t)row * 16 + 8 + i] = sn;
;     }
.LBB0_484:
	s_or_b64 exec, exec, s[2:3]
	v_ashrrev_i32_e32 v4, 3, v6
	v_ashrrev_i32_e32 v5, 31, v4
	v_lshl_add_u64 v[14:15], v[4:5], 2, s[10:11]
	global_load_dword v14, v[14:15], off nt
	s_waitcnt vmcnt(0)
	v_cvt_f32_i32_e32 v14, v14
	v_mul_f32_e32 v14, v0, v14
	v_and_b32_e32 v15, 0x7fffffff, v14
	v_cmp_nlt_f32_e64 s[2:3], |v14|, s1
	s_and_saveexec_b64 s[4:5], s[2:3]
	s_xor_b64 s[14:15], exec, s[4:5]
	s_cbranch_execz .LBB0_486
	v_lshrrev_b32_e32 v0, 23, v15
	v_add_u32_e32 v0, 0xffffff88, v0
	v_cmp_lt_u32_e32 vcc, 63, v0
	s_nop 1
	v_cndmask_b32_e32 v16, 0, v11, vcc
	v_add_u32_e32 v0, v16, v0
	v_cmp_lt_u32_e64 s[2:3], 31, v0
	s_nop 1
	v_cndmask_b32_e64 v16, 0, v12, s[2:3]
	v_add_u32_e32 v0, v16, v0
	v_cmp_lt_u32_e64 s[4:5], 31, v0
	s_nop 1
	v_cndmask_b32_e64 v16, 0, v12, s[4:5]
	v_add_u32_e32 v30, v16, v0
	v_and_b32_e32 v0, 0x7fffff, v15
	v_or_b32_e32 v28, 0x800000, v0
	v_mad_u64_u32 v[16:17], s[6:7], v28, s16, 0
	v_mov_b32_e32 v0, v17
	v_mad_u64_u32 v[18:19], s[6:7], v28, s17, v[0:1]
	v_mov_b32_e32 v0, v19
	v_mad_u64_u32 v[20:21], s[6:7], v28, s18, v[0:1]
	v_mov_b32_e32 v0, v21
	v_mad_u64_u32 v[22:23], s[6:7], v28, s19, v[0:1]
	v_mov_b32_e32 v0, v23
	v_mad_u64_u32 v[24:25], s[6:7], v28, s20, v[0:1]
	v_mov_b32_e32 v0, v25
	v_mad_u64_u32 v[26:27], s[6:7], v28, s21, v[0:1]
	v_mov_b32_e32 v0, v27
	v_mad_u64_u32 v[28:29], s[6:7], v28, s22, v[0:1]
	v_cndmask_b32_e32 v17, v26, v22, vcc
	v_cndmask_b32_e32 v0, v28, v24, vcc
	v_cndmask_b32_e32 v21, v29, v26, vcc
	v_cndmask_b32_e64 v19, v0, v17, s[2:3]
	v_cndmask_b32_e64 v0, v21, v0, s[2:3]
	v_cndmask_b32_e32 v21, v24, v20, vcc
	v_cndmask_b32_e64 v17, v17, v21, s[2:3]
	v_cndmask_b32_e64 v0, v0, v19, s[4:5]
	v_cndmask_b32_e64 v19, v19, v17, s[4:5]
	v_sub_u32_e32 v23, 32, v30
	v_alignbit_b32 v24, v0, v19, v23
	v_cmp_eq_u32_e64 s[6:7], 0, v30
	v_cndmask_b32_e32 v16, v20, v16, vcc
	s_nop 0
	v_cndmask_b32_e64 v24, v24, v0, s[6:7]
	v_cndmask_b32_e32 v0, v22, v18, vcc
	v_cndmask_b32_e64 v18, v21, v0, s[2:3]
	v_cndmask_b32_e64 v17, v17, v18, s[4:5]
	v_alignbit_b32 v21, v19, v17, v23
	v_cndmask_b32_e64 v19, v21, v19, s[6:7]
	v_bfe_u32 v25, v24, 29, 1
	v_cndmask_b32_e64 v0, v0, v16, s[2:3]
	v_alignbit_b32 v21, v24, v19, 30
	v_sub_u32_e32 v26, 0, v25
	v_cndmask_b32_e64 v0, v18, v0, s[4:5]
	v_xor_b32_e32 v21, v21, v26
	v_alignbit_b32 v16, v17, v0, v23
	v_cndmask_b32_e64 v16, v16, v17, s[6:7]
	v_ffbh_u32_e32 v18, v21
	v_alignbit_b32 v17, v19, v16, 30
	v_min_u32_e32 v18, 32, v18
	v_alignbit_b32 v0, v16, v0, 30
	v_xor_b32_e32 v17, v17, v26
	v_sub_u32_e32 v19, 31, v18
	v_xor_b32_e32 v0, v0, v26
	v_alignbit_b32 v20, v21, v17, v19
	v_alignbit_b32 v0, v17, v0, v19
	v_alignbit_b32 v16, v20, v0, 9
	v_ffbh_u32_e32 v17, v16
	v_min_u32_e32 v17, 32, v17
	v_lshrrev_b32_e32 v22, 29, v24
	v_not_b32_e32 v19, v17
	v_alignbit_b32 v0, v16, v0, v19
	v_lshlrev_b32_e32 v16, 31, v22
	v_or_b32_e32 v19, 0x33000000, v16
	v_add_lshl_u32 v17, v17, v18, 23
	v_lshrrev_b32_e32 v0, 9, v0
	v_sub_u32_e32 v17, v19, v17
	v_or_b32_e32 v16, 0.5, v16
	v_lshlrev_b32_e32 v18, 23, v18
	v_or_b32_e32 v0, v17, v0
	v_lshrrev_b32_e32 v17, 9, v20
	v_sub_u32_e32 v16, v16, v18
	v_or_b32_e32 v16, v17, v16
	v_mul_f32_e32 v17, 0x3fc90fda, v16
	v_fma_f32 v18, v16, s23, -v17
	v_fmac_f32_e32 v18, 0x33a22168, v16
	v_fmac_f32_e32 v18, 0x3fc90fda, v0
	v_lshrrev_b32_e32 v16, 30, v24
	v_add_f32_e32 v0, v17, v18
	v_add_u32_e32 v16, v25, v16
